# attention tile loop: O accumulators stay in place, per-tile v_mov copies removed
# speedup vs baseline: 1.0121x; 1.0121x over previous
.Lmy_attjoin_C:
	v_mov_b32_e32 v148, v152

; #define LAS __attribute__((address_space(3)))
; template <bool BAND>
; __device__ __forceinline__ void tile_body(f32x16* o, float& l_reg, const bf16x8* qr, const LAS unsigned char* kbs, const LAS float* wb, int vb, float ci, int hi, int keybase, int qabs) {
;     ...
; #pragma unroll
;     for (int g4 = 0; g4 < 4; ++g4) {
;         const f32x4 ba = *(const LAS f32x4*)(wb + 8 * g4 + 4 * hi) + ci, bb = *(const LAS f32x4*)(wb + 32 + 8 * g4 + 4 * hi) + ci;
; #pragma unroll
;         for (int e = 0; e < 4; ++e) { p0[4 * g4 + e] = ba[e]; p1[4 * g4 + e] = bb[e]; }
;     }
; #pragma unroll
;     for (int d0 = 0; d0 < 4; ++d0) {
;         const bf16x8 b0 = *(const LAS bf16x8*)(kbs + d0 * 2048), b1 = *(const LAS bf16x8*)(kbs + d0 * 2048 + 512);
;         p0 = __builtin_amdgcn_mfma_f32_32x32x16_bf16(b0, qr[d0], p0, 0, 0, 0); p1 = __builtin_amdgcn_mfma_f32_32x32x16_bf16(b1, qr[d0], p1, 0, 0, 0); }
.LBB0_783:
	s_andn2_saveexec_b64 s[12:13], s[12:13]
	v_mov_b32_e32 v149, s67
	v_add_f32_e32 v149, s28, v149
	v_add_f32_e32 v149, s66, v149
	s_or_b64 exec, exec, s[12:13]
	v_add_f32_e32 v149, v0, v149
	s_xor_b32 s74, s70, 1
	v_add_f32_e32 v0, v150, v149
	s_lshl_b32 s12, s74, 8
	v_sub_f32_e32 v0, v0, v140
	s_add_i32 s71, s53, s12
	s_lshl_b32 s78, s74, 14
	s_max_i32 s12, s48, 4
	v_mul_f32_e32 v140, 0x3fb8aa3b, v0
	v_lshl_add_u32 v0, v137, 2, s71
	v_readfirstlane_b32 s76, v149
	v_add_u32_e32 v149, s78, v143
	s_add_i32 s28, s12, -4
	ds_write_b32 v0, v140 offset:32768
	ds_write_b128 v149, v[66:69]
	ds_write_b128 v149, v[74:77] offset:8192
	s_lshl_b64 s[12:13], s[28:29], 11
	s_waitcnt lgkmcnt(0)
	v_lshl_add_u64 v[66:67], v[110:111], 0, s[12:13]
	s_lshl_b64 s[12:13], s[28:29], 16
	global_load_dword v140, v[66:67], off
	v_lshl_add_u64 v[74:75], v[106:107], 0, s[12:13]
	global_load_dwordx4 v[66:69], v[74:75], off
	v_cndmask_b32_e64 v74, 0, 1, s[58:59]
	v_lshl_add_u64 v[152:153], v[108:109], 0, s[12:13]
	v_cmp_ne_u32_e64 s[12:13], 1, v74
	global_load_dwordx4 v[74:77], v[152:153], off
	s_andn2_b64 vcc, exec, s[58:59]
	s_cbranch_vccnz .LBB0_792
	s_sub_i32 s28, s75, 64
	s_cmp_gt_i32 s28, s73
	s_cbranch_scc1 .LBB0_792
	s_lshl_b32 s64, s70, 8
	s_lshl_b32 s28, s70, 14
	s_add_i32 s66, s53, s64
	s_cmp_lt_i32 s48, s72
	v_add_u32_e32 v151, s28, v144
	s_mov_b64 s[64:65], -1
	v_add_u32_e32 v152, s28, v145
	v_lshl_add_u32 v153, v142, 2, s66
	s_cbranch_scc1 .LBB0_789
	ds_read_b128 v[34:37], v153 offset:32768
	ds_read_b128 v[38:41], v153 offset:32800
	ds_read_b128 v[42:45], v153 offset:32832
	ds_read_b128 v[46:49], v153 offset:32864
	ds_read_b128 v[50:53], v153 offset:32896
	ds_read_b128 v[54:57], v153 offset:32928
	ds_read_b128 v[58:61], v153 offset:32960
	ds_read_b128 v[62:65], v153 offset:32992
	ds_read_b128 v[154:157], v152
	ds_read_b128 v[158:161], v152 offset:512
	s_waitcnt lgkmcnt(4)
	v_pk_add_f32 v[56:57], v[118:119], v[56:57]
	s_waitcnt lgkmcnt(3)
	v_pk_add_f32 v[60:61], v[122:123], v[60:61]
	s_waitcnt lgkmcnt(2)
	v_pk_add_f32 v[64:65], v[126:127], v[64:65]
	v_pk_add_f32 v[52:53], v[114:115], v[52:53]
	v_pk_add_f32 v[62:63], v[124:125], v[62:63]
	v_pk_add_f32 v[58:59], v[120:121], v[58:59]
	v_pk_add_f32 v[54:55], v[116:117], v[54:55]
	v_pk_add_f32 v[50:51], v[112:113], v[50:51]
	v_pk_add_f32 v[48:49], v[126:127], v[48:49]
	v_pk_add_f32 v[44:45], v[122:123], v[44:45]
	v_pk_add_f32 v[40:41], v[118:119], v[40:41]
	v_pk_add_f32 v[36:37], v[114:115], v[36:37]
	v_pk_add_f32 v[46:47], v[124:125], v[46:47]
	v_pk_add_f32 v[42:43], v[120:121], v[42:43]
	v_pk_add_f32 v[38:39], v[116:117], v[38:39]
	v_pk_add_f32 v[34:35], v[112:113], v[34:35]
	s_waitcnt lgkmcnt(0)
	v_mfma_f32_32x32x16_bf16 v[50:65], v[158:161], v[94:97], v[50:65]
	v_mfma_f32_32x32x16_bf16 v[34:49], v[154:157], v[94:97], v[34:49]
	ds_read_b128 v[154:157], v152 offset:2048
	ds_read_b128 v[158:161], v152 offset:2560
	s_waitcnt lgkmcnt(0)
	v_mfma_f32_32x32x16_bf16 v[50:65], v[158:161], v[98:101], v[50:65]
	v_mfma_f32_32x32x16_bf16 v[34:49], v[154:157], v[98:101], v[34:49]
	ds_read_b128 v[154:157], v152 offset:4096
	ds_read_b128 v[158:161], v152 offset:4608
	s_waitcnt lgkmcnt(0)
	v_mfma_f32_32x32x16_bf16 v[50:65], v[158:161], v[102:105], v[50:65]
	v_mfma_f32_32x32x16_bf16 v[34:49], v[154:157], v[102:105], v[34:49]
	ds_read_b128 v[154:157], v152 offset:6656
	ds_read_b128 v[158:161], v152 offset:6144
	s_waitcnt lgkmcnt(1)
	v_mfma_f32_32x32x16_bf16 v[50:65], v[154:157], v[90:93], v[50:65]
	v_add_u32_e32 v154, s75, v142
	v_subrev_u32_e32 v156, 32, v154
	v_subrev_u32_e32 v155, 64, v154
	v_cmp_le_i32_e32 vcc, v156, v147
	s_waitcnt lgkmcnt(0)
; __device__ __forceinline__ void pv(f32x16* o, int vb, bf16x8 pa0, bf16x8 pa1, bf16x8 pa2, bf16x8 pa3) {
; #pragma unroll
;     for (int d0 = 0; d0 < 2; ++d0) { s16x4 lo[4], hi[4];
; #pragma unroll
;         for (int ks = 0; ks < 4; ++ks) {
;             asm volatile("ds_read_b64_tr_b16 %0,%1 offset:%c2" : "=&v"(lo[ks]) : "v"(vb), "i"(d0 * 4096 + ks * 1024) : "memory");
;             asm volatile("ds_read_b64_tr_b16 %0,%1 offset:%c2" : "=&v"(hi[ks]) : "v"(vb), "i"(d0 * 4096 + ks * 1024 + 512) : "memory"); }
;         asm volatile("s_waitcnt lgkmcnt(0)" ::: "memory"); __builtin_amdgcn_sched_barrier(0);
;     ...
;         o[d0] = __builtin_amdgcn_mfma_f32_32x32x16_bf16(pa0, PK(0), o[d0], 0, 0, 0);
;         o[d0] = __builtin_amdgcn_mfma_f32_32x32x16_bf16(pa1, PK(1), o[d0], 0, 0, 0);
;         o[d0] = __builtin_amdgcn_mfma_f32_32x32x16_bf16(pa2, PK(2), o[d0], 0, 0, 0);
;         o[d0] = __builtin_amdgcn_mfma_f32_32x32x16_bf16(pa3, PK(3), o[d0], 0, 0, 0);
; template <bool BAND>
; __device__ __forceinline__ void tile_body(f32x16* o, float& l_reg, const bf16x8* qr, const LAS unsigned char* kbs, const LAS float* wb, int vb, float ci, int hi, int keybase, int qabs) {
;     ...
;     if (BAND) {
; #pragma unroll
;         for (int r = 0; r < 16; ++r) { const int key = keybase + 8 * (r >> 2) + (r & 3); if (key > qabs) p0[r] = -INFINITY; if (key + 32 > qabs) p1[r] = -INFINITY; }
;     }
;     f32x2 s2 = {0.f, 0.f};
; #pragma unroll
;     for (int r = 0; r < 16; r += 2) {
;         p0[r] = __builtin_amdgcn_exp2f(p0[r]); p0[r + 1] = __builtin_amdgcn_exp2f(p0[r + 1]); p1[r] = __builtin_amdgcn_exp2f(p1[r]); p1[r + 1] = __builtin_amdgcn_exp2f(p1[r + 1]);
;         s2 += (f32x2){p0[r], p0[r + 1]}; s2 += (f32x2){p1[r], p1[r + 1]}; }
;     l_reg += s2.x + s2.y;
;     u32x4 pw0, pw1, pw2, pw3;
;     pw0 = (u32x4){cvtpk(p0[0], p0[1]), cvtpk(p0[2], p0[3]), cvtpk(p0[4], p0[5]), cvtpk(p0[6], p0[7])};
;     pw1 = (u32x4){cvtpk(p0[8], p0[9]), cvtpk(p0[10], p0[11]), cvtpk(p0[12], p0[13]), cvtpk(p0[14], p0[15])};
;     pw2 = (u32x4){cvtpk(p1[0], p1[1]), cvtpk(p1[2], p1[3]), cvtpk(p1[4], p1[5]), cvtpk(p1[6], p1[7])};
;     pw3 = (u32x4){cvtpk(p1[8], p1[9]), cvtpk(p1[10], p1[11]), cvtpk(p1[12], p1[13]), cvtpk(p1[14], p1[15])};
;     pv(o, vb, __builtin_bit_cast(bf16x8, pw0), __builtin_bit_cast(bf16x8, pw1), __builtin_bit_cast(bf16x8, pw2), __builtin_bit_cast(bf16x8, pw3));
	v_mfma_f32_32x32x16_bf16 v[34:49], v[158:161], v[90:93], v[34:49]
	s_nop 5
	v_cndmask_b32_e32 v50, v134, v50, vcc
	v_cmp_lt_i32_e32 vcc, v155, v147
	s_nop 3
	v_cndmask_b32_e32 v35, v134, v35, vcc
	v_cmp_le_i32_e32 vcc, v155, v147
	v_subrev_u32_e32 v155, 31, v154
	v_exp_f32_e32 v35, v35
	v_cndmask_b32_e32 v34, v134, v34, vcc
	v_cmp_le_i32_e32 vcc, v155, v147
	v_subrev_u32_e32 v155, 62, v154
	v_exp_f32_e32 v34, v34
	v_cndmask_b32_e32 v51, v134, v51, vcc
	v_cmp_le_i32_e32 vcc, v155, v147
	s_nop 1
	v_cndmask_b32_e32 v155, v134, v36, vcc
	v_subrev_u32_e32 v36, 30, v154
	v_cmp_le_i32_e32 vcc, v36, v147
	v_subrev_u32_e32 v36, 61, v154
	s_nop 0
	v_cndmask_b32_e32 v52, v134, v52, vcc
	v_cmp_le_i32_e32 vcc, v36, v147
	v_subrev_u32_e32 v36, 29, v154
	s_nop 0
	v_cndmask_b32_e32 v156, v134, v37, vcc
	v_cmp_le_i32_e32 vcc, v36, v147
	v_subrev_u32_e32 v36, 56, v154
	v_exp_f32_e32 v37, v51
	v_cndmask_b32_e32 v53, v134, v53, vcc
	v_cmp_le_i32_e32 vcc, v36, v147
	v_subrev_u32_e32 v36, 24, v154
	s_nop 0
	v_cndmask_b32_e32 v157, v134, v38, vcc
	v_cmp_le_i32_e32 vcc, v36, v147
	v_subrev_u32_e32 v36, 55, v154
	v_exp_f32_e32 v38, v155
	v_cndmask_b32_e32 v54, v134, v54, vcc
	v_cmp_le_i32_e32 vcc, v36, v147
	v_subrev_u32_e32 v36, 23, v154
	s_nop 0
	v_cndmask_b32_e32 v158, v134, v39, vcc
	v_cmp_le_i32_e32 vcc, v36, v147
	v_subrev_u32_e32 v36, 54, v154
	v_exp_f32_e32 v39, v156
	v_cndmask_b32_e32 v55, v134, v55, vcc
	v_cmp_le_i32_e32 vcc, v36, v147
	v_subrev_u32_e32 v36, 22, v154
	v_cvt_pk_bf16_f32 v156, v34, v35
	v_cndmask_b32_e32 v159, v134, v40, vcc
	v_cmp_le_i32_e32 vcc, v36, v147
	v_subrev_u32_e32 v36, 53, v154
	v_exp_f32_e32 v40, v52
	v_cndmask_b32_e32 v56, v134, v56, vcc
	v_cmp_le_i32_e32 vcc, v36, v147
	v_subrev_u32_e32 v36, 21, v154
	s_nop 0
	v_cndmask_b32_e32 v160, v134, v41, vcc
	v_cmp_le_i32_e32 vcc, v36, v147
	v_subrev_u32_e32 v36, 48, v154
	v_exp_f32_e32 v41, v53
	v_cndmask_b32_e32 v57, v134, v57, vcc
	v_cmp_le_i32_e32 vcc, v36, v147
	v_add_u32_e32 v36, -16, v154
	v_exp_f32_e32 v51, v57
	v_cndmask_b32_e32 v161, v134, v42, vcc
	v_cmp_le_i32_e32 vcc, v36, v147
	v_subrev_u32_e32 v36, 47, v154
	v_exp_f32_e32 v52, v161
	v_cndmask_b32_e32 v58, v134, v58, vcc
	v_cmp_le_i32_e32 vcc, v36, v147
	v_add_u32_e32 v36, -15, v154
	s_nop 0
	v_cndmask_b32_e32 v162, v134, v43, vcc
	v_cmp_le_i32_e32 vcc, v36, v147
	v_subrev_u32_e32 v36, 46, v154
	v_pk_add_f32 v[42:43], v[34:35], 0 op_sel_hi:[1,0]
	v_cndmask_b32_e32 v59, v134, v59, vcc
	v_cmp_le_i32_e32 vcc, v36, v147
	v_add_u32_e32 v36, -14, v154
	v_exp_f32_e32 v53, v162
	v_cndmask_b32_e32 v163, v134, v44, vcc
	v_cmp_le_i32_e32 vcc, v36, v147
	v_subrev_u32_e32 v36, 45, v154
	v_exp_f32_e32 v44, v157
	v_cndmask_b32_e32 v60, v134, v60, vcc
	v_cmp_le_i32_e32 vcc, v36, v147
	v_add_u32_e32 v36, -13, v154
	v_cvt_pk_bf16_f32 v157, v38, v39
	v_cndmask_b32_e32 v164, v134, v45, vcc
	v_cmp_le_i32_e32 vcc, v36, v147
	v_subrev_u32_e32 v36, 40, v154
	v_exp_f32_e32 v45, v158
	v_cndmask_b32_e32 v61, v134, v61, vcc
	v_cmp_le_i32_e32 vcc, v36, v147
	v_add_u32_e32 v36, -8, v154
	v_exp_f32_e32 v57, v164
	v_cndmask_b32_e32 v165, v134, v46, vcc
	v_cmp_le_i32_e32 vcc, v36, v147
	v_subrev_u32_e32 v36, 39, v154
	v_exp_f32_e32 v46, v54
	v_cndmask_b32_e32 v62, v134, v62, vcc
	v_cmp_le_i32_e32 vcc, v36, v147
	v_add_u32_e32 v36, -7, v154
	v_exp_f32_e32 v54, v58
	v_cndmask_b32_e32 v166, v134, v47, vcc
	v_cmp_le_i32_e32 vcc, v36, v147
	v_subrev_u32_e32 v36, 38, v154
	v_exp_f32_e32 v47, v55
	v_cndmask_b32_e32 v63, v134, v63, vcc
	v_cmp_le_i32_e32 vcc, v36, v147
	v_add_u32_e32 v36, -6, v154
	v_exp_f32_e32 v55, v59
	v_cndmask_b32_e32 v167, v134, v48, vcc
	v_cmp_le_i32_e32 vcc, v36, v147
	v_subrev_u32_e32 v36, 37, v154
	v_exp_f32_e32 v48, v159
	v_cndmask_b32_e32 v168, v134, v64, vcc
	v_cmp_le_i32_e32 vcc, v36, v147
	v_add_u32_e32 v36, -5, v154
	v_exp_f32_e32 v58, v60
	v_cndmask_b32_e32 v169, v134, v49, vcc
	v_cmp_le_i32_e32 vcc, v36, v147
	v_exp_f32_e32 v36, v50
	v_exp_f32_e32 v49, v160
	v_exp_f32_e32 v50, v56
	v_exp_f32_e32 v56, v163
	v_pk_add_f32 v[42:43], v[36:37], v[42:43]
	v_exp_f32_e32 v59, v61
	v_pk_add_f32 v[42:43], v[38:39], v[42:43]
	v_exp_f32_e32 v64, v167
	v_pk_add_f32 v[42:43], v[40:41], v[42:43]
	v_cvt_pk_bf16_f32 v167, v50, v51
	v_pk_add_f32 v[42:43], v[44:45], v[42:43]
	v_exp_f32_e32 v60, v165
	v_pk_add_f32 v[42:43], v[46:47], v[42:43]
	v_exp_f32_e32 v61, v166
	v_pk_add_f32 v[42:43], v[48:49], v[42:43]
	v_cvt_pk_bf16_f32 v160, v52, v53
	v_pk_add_f32 v[42:43], v[50:51], v[42:43]
	ds_read_b64_tr_b16 v[50:51],v151 offset:0
	v_exp_f32_e32 v62, v62
	v_pk_add_f32 v[42:43], v[52:53], v[42:43]
	ds_read_b64_tr_b16 v[52:53],v151 offset:512
	v_exp_f32_e32 v63, v63
	v_pk_add_f32 v[42:43], v[54:55], v[42:43]
	v_exp_f32_e32 v172, v168
	v_cvt_pk_bf16_f32 v168, v54, v55
	ds_read_b64_tr_b16 v[54:55],v151 offset:1024
	v_cndmask_b32_e32 v154, v134, v65, vcc
	v_pk_add_f32 v[42:43], v[56:57], v[42:43]
	v_exp_f32_e32 v65, v169
	v_cvt_pk_bf16_f32 v161, v56, v57
	ds_read_b64_tr_b16 v[56:57],v151 offset:1536
	v_pk_add_f32 v[42:43], v[58:59], v[42:43]
	v_exp_f32_e32 v173, v154
	v_cvt_pk_bf16_f32 v169, v58, v59
	ds_read_b64_tr_b16 v[58:59],v151 offset:2048
	v_pk_add_f32 v[42:43], v[60:61], v[42:43]
	v_cvt_pk_bf16_f32 v162, v60, v61
	ds_read_b64_tr_b16 v[60:61],v151 offset:2560
	v_pk_add_f32 v[42:43], v[62:63], v[42:43]
	v_cvt_pk_bf16_f32 v170, v62, v63
	ds_read_b64_tr_b16 v[62:63],v151 offset:3072
	v_pk_add_f32 v[42:43], v[64:65], v[42:43]
	v_cvt_pk_bf16_f32 v163, v64, v65
	ds_read_b64_tr_b16 v[64:65],v151 offset:3584
	v_pk_add_f32 v[42:43], v[172:173], v[42:43]
	s_waitcnt lgkmcnt(0)
	v_cvt_pk_bf16_f32 v158, v44, v45
	v_add_f32_e32 v42, v42, v43
	v_add_f32_e32 v154, v148, v42
	v_cvt_pk_bf16_f32 v159, v48, v49
	v_cvt_pk_bf16_f32 v164, v36, v37
	v_cvt_pk_bf16_f32 v165, v40, v41
	v_cvt_pk_bf16_f32 v166, v46, v47
	v_cvt_pk_bf16_f32 v171, v172, v173
	v_mfma_f32_32x32x16_bf16 v[2:17], v[156:159], v[50:53], v[2:17]
	ds_read_b64_tr_b16 v[172:173],v151 offset:4096
	ds_read_b64_tr_b16 v[174:175],v151 offset:4608
	ds_read_b64_tr_b16 v[176:177],v151 offset:5120
	ds_read_b64_tr_b16 v[178:179],v151 offset:5632
	ds_read_b64_tr_b16 v[180:181],v151 offset:6144
	ds_read_b64_tr_b16 v[182:183],v151 offset:6656
	ds_read_b64_tr_b16 v[184:185],v151 offset:7168
	v_mfma_f32_32x32x16_bf16 v[2:17], v[160:163], v[54:57], v[2:17]
	ds_read_b64_tr_b16 v[186:187],v151 offset:7680
	s_waitcnt lgkmcnt(0)
	v_mfma_f32_32x32x16_bf16 v[2:17], v[164:167], v[58:61], v[2:17]
	v_mfma_f32_32x32x16_bf16 v[2:17], v[168:171], v[62:65], v[2:17]
	v_mfma_f32_32x32x16_bf16 v[18:33], v[156:159], v[172:175], v[18:33]
	s_mov_b64 s[64:65], 0
	v_mfma_f32_32x32x16_bf16 v[18:33], v[160:163], v[176:179], v[18:33]
	v_mfma_f32_32x32x16_bf16 v[18:33], v[164:167], v[180:183], v[18:33]
	v_mfma_f32_32x32x16_bf16 v[18:33], v[168:171], v[184:187], v[18:33]

; __device__ __forceinline__ void attn_unit(const UnitDesc& u, LAS unsigned char* shm, float qkmax, float thresh) {
;     ...
;     for (;;) {
;         ATT_ITER(kA, vA, lA); if (stop) break;
;         ATT_ITER(kB, vB, lB); if (stop) break;
;         ATT_ITER(kC, vC, lC); if (stop) break;
;     }
.Lmy_attjoin_A:
	v_mov_b32_e32 v148, v154

.LBB0_799:
	s_andn2_saveexec_b64 s[66:67], s[66:67]
	v_mov_b32_e32 v151, s79
	v_add_f32_e32 v151, s28, v151
	v_add_f32_e32 v153, s77, v151
	s_or_b64 exec, exec, s[66:67]
	v_add_f32_e32 v151, s76, v150
	v_add_f32_e32 v150, v152, v153
	v_add_f32_e32 v152, v151, v150
	s_lshl_b32 s28, s70, 8
	v_sub_f32_e32 v141, v152, v141
	s_add_i32 s76, s53, s28
	v_mul_f32_e32 v141, 0x3fb8aa3b, v141
	v_lshl_add_u32 v152, v137, 2, s76
	s_lshl_b32 s77, s70, 14
	ds_write_b32 v152, v141 offset:32768
	v_add_u32_e32 v141, s77, v143
	s_max_i32 s28, s48, 5
	ds_write_b128 v141, v[70:73]
	ds_write_b128 v141, v[82:85] offset:8192
	s_add_i32 s28, s28, -5
	s_waitcnt lgkmcnt(0)
	s_lshl_b64 s[66:67], s[28:29], 11
	v_lshl_add_u64 v[70:71], v[110:111], 0, s[66:67]
	global_load_dword v141, v[70:71], off
	s_lshl_b64 s[66:67], s[28:29], 16
	v_lshl_add_u64 v[82:83], v[106:107], 0, s[66:67]
	global_load_dwordx4 v[70:73], v[82:83], off
	v_lshl_add_u64 v[152:153], v[108:109], 0, s[66:67]
	global_load_dwordx4 v[82:85], v[152:153], off
	v_readfirstlane_b32 s79, v150
	s_and_b64 vcc, exec, s[12:13]
	s_cbranch_vccnz .LBB0_808
	s_add_i32 s28, s75, 0xffffff80
	s_cmp_gt_i32 s28, s73
	s_cbranch_scc1 .LBB0_808
	s_cmp_le_i32 s48, s72
	v_add_u32_e32 v150, s78, v144
	s_mov_b64 s[66:67], -1
	v_add_u32_e32 v152, s78, v145
	v_lshl_add_u32 v153, v142, 2, s71
	s_cbranch_scc0 .LBB0_805
; #define LAS __attribute__((address_space(3)))
; __device__ __forceinline__ void pv(f32x16* o, int vb, bf16x8 pa0, bf16x8 pa1, bf16x8 pa2, bf16x8 pa3) {
; #pragma unroll
;     for (int d0 = 0; d0 < 2; ++d0) { s16x4 lo[4], hi[4];
; #pragma unroll
;         for (int ks = 0; ks < 4; ++ks) {
; template <bool BAND>
; __device__ __forceinline__ void tile_body(f32x16* o, float& l_reg, const bf16x8* qr, const LAS unsigned char* kbs, const LAS float* wb, int vb, float ci, int hi, int keybase, int qabs) {
;     ...
; #pragma unroll
;     for (int g4 = 0; g4 < 4; ++g4) {
;         const f32x4 ba = *(const LAS f32x4*)(wb + 8 * g4 + 4 * hi) + ci, bb = *(const LAS f32x4*)(wb + 32 + 8 * g4 + 4 * hi) + ci;
; #pragma unroll
;         for (int e = 0; e < 4; ++e) { p0[4 * g4 + e] = ba[e]; p1[4 * g4 + e] = bb[e]; }
;     }
; #pragma unroll
;     for (int d0 = 0; d0 < 4; ++d0) {
;         const bf16x8 b0 = *(const LAS bf16x8*)(kbs + d0 * 2048), b1 = *(const LAS bf16x8*)(kbs + d0 * 2048 + 512);
;         p0 = __builtin_amdgcn_mfma_f32_32x32x16_bf16(b0, qr[d0], p0, 0, 0, 0); p1 = __builtin_amdgcn_mfma_f32_32x32x16_bf16(b1, qr[d0], p1, 0, 0, 0); }
;     if (BAND) {
; #pragma unroll
;         for (int r = 0; r < 16; ++r) { const int key = keybase + 8 * (r >> 2) + (r & 3); if (key > qabs) p0[r] = -INFINITY; if (key + 32 > qabs) p1[r] = -INFINITY; }
;     }
;     f32x2 s2 = {0.f, 0.f};
; #pragma unroll
;     for (int r = 0; r < 16; r += 2) {
;         p0[r] = __builtin_amdgcn_exp2f(p0[r]); p0[r + 1] = __builtin_amdgcn_exp2f(p0[r + 1]); p1[r] = __builtin_amdgcn_exp2f(p1[r]); p1[r + 1] = __builtin_amdgcn_exp2f(p1[r + 1]);
;         s2 += (f32x2){p0[r], p0[r + 1]}; s2 += (f32x2){p1[r], p1[r + 1]}; }
;     l_reg += s2.x + s2.y;
;     u32x4 pw0, pw1, pw2, pw3;
;     pw0 = (u32x4){cvtpk(p0[0], p0[1]), cvtpk(p0[2], p0[3]), cvtpk(p0[4], p0[5]), cvtpk(p0[6], p0[7])};
;     pw1 = (u32x4){cvtpk(p0[8], p0[9]), cvtpk(p0[10], p0[11]), cvtpk(p0[12], p0[13]), cvtpk(p0[14], p0[15])};
;     pw2 = (u32x4){cvtpk(p1[0], p1[1]), cvtpk(p1[2], p1[3]), cvtpk(p1[4], p1[5]), cvtpk(p1[6], p1[7])};
;     pw3 = (u32x4){cvtpk(p1[8], p1[9]), cvtpk(p1[10], p1[11]), cvtpk(p1[12], p1[13]), cvtpk(p1[14], p1[15])};
;     pv(o, vb, __builtin_bit_cast(bf16x8, pw0), __builtin_bit_cast(bf16x8, pw1), __builtin_bit_cast(bf16x8, pw2), __builtin_bit_cast(bf16x8, pw3));
	ds_read_b128 v[34:37], v153 offset:32768
	ds_read_b128 v[38:41], v153 offset:32800
	ds_read_b128 v[42:45], v153 offset:32832
	ds_read_b128 v[46:49], v153 offset:32864
	ds_read_b128 v[50:53], v153 offset:32896
	ds_read_b128 v[54:57], v153 offset:32928
	ds_read_b128 v[58:61], v153 offset:32960
	ds_read_b128 v[62:65], v153 offset:32992
	ds_read_b128 v[154:157], v152
	ds_read_b128 v[158:161], v152 offset:512
	s_waitcnt lgkmcnt(6)
	v_pk_add_f32 v[48:49], v[126:127], v[48:49]
	v_pk_add_f32 v[44:45], v[122:123], v[44:45]
	v_pk_add_f32 v[40:41], v[118:119], v[40:41]
	v_pk_add_f32 v[36:37], v[114:115], v[36:37]
	v_pk_add_f32 v[46:47], v[124:125], v[46:47]
	v_pk_add_f32 v[42:43], v[120:121], v[42:43]
	v_pk_add_f32 v[38:39], v[116:117], v[38:39]
	v_pk_add_f32 v[34:35], v[112:113], v[34:35]
	s_waitcnt lgkmcnt(2)
	v_pk_add_f32 v[64:65], v[126:127], v[64:65]
	v_pk_add_f32 v[60:61], v[122:123], v[60:61]
	s_waitcnt lgkmcnt(1)
	v_mfma_f32_32x32x16_bf16 v[34:49], v[154:157], v[94:97], v[34:49]
	v_add_f32_e64 v56, v118, v56
	v_add_f32_e64 v57, v119, v57
	v_add_f32_e64 v52, v114, v52
	v_add_f32_e64 v53, v115, v53
	v_add_f32_e64 v62, v124, v62
	v_add_f32_e64 v63, v125, v63
	v_pk_add_f32 v[58:59], v[120:121], v[58:59]
	v_pk_add_f32 v[54:55], v[116:117], v[54:55]
	v_pk_add_f32 v[50:51], v[112:113], v[50:51]
	s_waitcnt lgkmcnt(0)
	s_nop 0
	v_mfma_f32_32x32x16_bf16 v[50:65], v[158:161], v[94:97], v[50:65]
	ds_read_b128 v[154:157], v152 offset:2048
	ds_read_b128 v[158:161], v152 offset:2560
	s_waitcnt lgkmcnt(1)
	v_mfma_f32_32x32x16_bf16 v[34:49], v[154:157], v[98:101], v[34:49]
	s_waitcnt lgkmcnt(0)
	v_mfma_f32_32x32x16_bf16 v[50:65], v[158:161], v[98:101], v[50:65]
	ds_read_b128 v[154:157], v152 offset:4096
	ds_read_b128 v[158:161], v152 offset:4608
	s_waitcnt lgkmcnt(1)
	v_mfma_f32_32x32x16_bf16 v[34:49], v[154:157], v[102:105], v[34:49]
	s_waitcnt lgkmcnt(0)
	v_mfma_f32_32x32x16_bf16 v[50:65], v[158:161], v[102:105], v[50:65]
	ds_read_b128 v[154:157], v152 offset:6144
	ds_read_b128 v[158:161], v152 offset:6656
	s_waitcnt lgkmcnt(1)
	v_mfma_f32_32x32x16_bf16 v[34:49], v[154:157], v[90:93], v[34:49]
	s_waitcnt lgkmcnt(0)
	v_mfma_f32_32x32x16_bf16 v[50:65], v[158:161], v[90:93], v[50:65]
	s_nop 9
	v_exp_f32_e32 v34, v34
	v_exp_f32_e32 v35, v35
	v_exp_f32_e32 v36, v36
	v_exp_f32_e32 v37, v37
	v_exp_f32_e32 v38, v38
	v_pk_add_f32 v[154:155], v[34:35], 0 op_sel_hi:[1,0]
	v_exp_f32_e32 v39, v39
	v_exp_f32_e32 v50, v50
	v_exp_f32_e32 v51, v51
	v_exp_f32_e32 v52, v52
	v_exp_f32_e32 v53, v53
	v_exp_f32_e32 v54, v54
	v_pk_add_f32 v[154:155], v[50:51], v[154:155]
	v_exp_f32_e32 v55, v55
	v_pk_add_f32 v[154:155], v[36:37], v[154:155]
	v_exp_f32_e32 v40, v40
	v_exp_f32_e32 v41, v41
	v_pk_add_f32 v[154:155], v[52:53], v[154:155]
	v_exp_f32_e32 v56, v56
	v_exp_f32_e32 v57, v57
	v_pk_add_f32 v[154:155], v[38:39], v[154:155]
	v_exp_f32_e32 v42, v42
	v_exp_f32_e32 v43, v43
	v_pk_add_f32 v[154:155], v[54:55], v[154:155]
	v_exp_f32_e32 v58, v58
	v_exp_f32_e32 v59, v59
	v_pk_add_f32 v[154:155], v[40:41], v[154:155]
	v_exp_f32_e32 v44, v44
	v_exp_f32_e32 v45, v45
	v_pk_add_f32 v[154:155], v[56:57], v[154:155]
	v_exp_f32_e32 v60, v60
	v_exp_f32_e32 v61, v61
	v_pk_add_f32 v[154:155], v[42:43], v[154:155]
	v_exp_f32_e32 v46, v46
	v_exp_f32_e32 v47, v47
	v_cvt_pk_bf16_f32 v164, v50, v51
	ds_read_b64_tr_b16 v[50:51],v150 offset:0
	v_pk_add_f32 v[154:155], v[58:59], v[154:155]
	v_exp_f32_e32 v62, v62
	v_exp_f32_e32 v63, v63
	v_cvt_pk_bf16_f32 v165, v52, v53
	ds_read_b64_tr_b16 v[52:53],v150 offset:512
	v_pk_add_f32 v[154:155], v[44:45], v[154:155]
	v_exp_f32_e32 v48, v48
	v_exp_f32_e32 v49, v49
	v_cvt_pk_bf16_f32 v166, v54, v55
	ds_read_b64_tr_b16 v[54:55],v150 offset:1024
	v_pk_add_f32 v[154:155], v[60:61], v[154:155]
	v_exp_f32_e32 v64, v64
	v_exp_f32_e32 v65, v65
	v_cvt_pk_bf16_f32 v167, v56, v57
	ds_read_b64_tr_b16 v[56:57],v150 offset:1536
	v_pk_add_f32 v[154:155], v[46:47], v[154:155]
	v_cvt_pk_bf16_f32 v168, v58, v59
	ds_read_b64_tr_b16 v[58:59],v150 offset:2048
	v_pk_add_f32 v[154:155], v[62:63], v[154:155]
	v_cvt_pk_bf16_f32 v169, v60, v61
	ds_read_b64_tr_b16 v[60:61],v150 offset:2560
	v_pk_add_f32 v[154:155], v[48:49], v[154:155]
	v_cvt_pk_bf16_f32 v170, v62, v63
	ds_read_b64_tr_b16 v[62:63],v150 offset:3072
	v_pk_add_f32 v[154:155], v[64:65], v[154:155]
	v_cvt_pk_bf16_f32 v171, v64, v65
	ds_read_b64_tr_b16 v[64:65],v150 offset:3584
	s_waitcnt lgkmcnt(0)
	v_add_f32_e32 v154, v154, v155
	v_add_f32_e32 v154, v148, v154
	v_cvt_pk_bf16_f32 v156, v34, v35
	v_cvt_pk_bf16_f32 v157, v36, v37
	v_cvt_pk_bf16_f32 v158, v38, v39
	v_cvt_pk_bf16_f32 v159, v40, v41
	v_cvt_pk_bf16_f32 v160, v42, v43
	v_cvt_pk_bf16_f32 v161, v44, v45
	v_cvt_pk_bf16_f32 v162, v46, v47
	v_cvt_pk_bf16_f32 v163, v48, v49
	v_mfma_f32_32x32x16_bf16 v[2:17], v[156:159], v[50:53], v[2:17]
	ds_read_b64_tr_b16 v[172:173],v150 offset:4096
	ds_read_b64_tr_b16 v[174:175],v150 offset:4608
	ds_read_b64_tr_b16 v[176:177],v150 offset:5120
	ds_read_b64_tr_b16 v[178:179],v150 offset:5632
	ds_read_b64_tr_b16 v[180:181],v150 offset:6144
	ds_read_b64_tr_b16 v[182:183],v150 offset:6656
	ds_read_b64_tr_b16 v[184:185],v150 offset:7168
	s_nop 0
	v_mfma_f32_32x32x16_bf16 v[2:17], v[160:163], v[54:57], v[2:17]
	ds_read_b64_tr_b16 v[186:187],v150 offset:7680
	s_waitcnt lgkmcnt(0)
	v_mfma_f32_32x32x16_bf16 v[2:17], v[164:167], v[58:61], v[2:17]
	v_mfma_f32_32x32x16_bf16 v[2:17], v[168:171], v[62:65], v[2:17]
	v_mfma_f32_32x32x16_bf16 v[18:33], v[156:159], v[172:175], v[18:33]
	s_mov_b64 s[66:67], 0
	v_mfma_f32_32x32x16_bf16 v[18:33], v[160:163], v[176:179], v[18:33]
	v_mfma_f32_32x32x16_bf16 v[18:33], v[164:167], v[180:183], v[18:33]
	v_mfma_f32_32x32x16_bf16 v[18:33], v[168:171], v[184:187], v[18:33]

; #define LAS __attribute__((address_space(3)))
; template <bool BAND>
; __device__ __forceinline__ void tile_body(f32x16* o, float& l_reg, const bf16x8* qr, const LAS unsigned char* kbs, const LAS float* wb, int vb, float ci, int hi, int keybase, int qabs) {
;     ...
; #pragma unroll
;     for (int g4 = 0; g4 < 4; ++g4) {
;         const f32x4 ba = *(const LAS f32x4*)(wb + 8 * g4 + 4 * hi) + ci, bb = *(const LAS f32x4*)(wb + 32 + 8 * g4 + 4 * hi) + ci;
; #pragma unroll
;         for (int e = 0; e < 4; ++e) { p0[4 * g4 + e] = ba[e]; p1[4 * g4 + e] = bb[e]; }
;     }
; #pragma unroll
;     for (int d0 = 0; d0 < 4; ++d0) {
;         const bf16x8 b0 = *(const LAS bf16x8*)(kbs + d0 * 2048), b1 = *(const LAS bf16x8*)(kbs + d0 * 2048 + 512);
;         p0 = __builtin_amdgcn_mfma_f32_32x32x16_bf16(b0, qr[d0], p0, 0, 0, 0); p1 = __builtin_amdgcn_mfma_f32_32x32x16_bf16(b1, qr[d0], p1, 0, 0, 0); }
;     if (BAND) {
; #pragma unroll
;         for (int r = 0; r < 16; ++r) { const int key = keybase + 8 * (r >> 2) + (r & 3); if (key > qabs) p0[r] = -INFINITY; if (key + 32 > qabs) p1[r] = -INFINITY; }
.LBB0_819:
	s_andn2_b64 vcc, exec, s[68:69]
	s_cbranch_vccnz .LBB0_774
	s_add_i32 s28, s75, 0xffffff40
	s_cmp_gt_i32 s28, s73
	s_cbranch_scc1 .LBB0_774
	s_add_i32 s68, s48, -2
	s_cmp_lt_i32 s68, s72
	v_add_u32_e32 v0, s77, v144
	s_mov_b64 s[68:69], -1
	v_add_u32_e32 v149, s77, v145
	v_lshl_add_u32 v150, v142, 2, s76
	s_cbranch_scc1 .LBB0_823
	ds_read_b128 v[34:37], v150 offset:32768
	ds_read_b128 v[38:41], v150 offset:32800
	ds_read_b128 v[42:45], v150 offset:32832
	ds_read_b128 v[46:49], v150 offset:32864
	ds_read_b128 v[50:53], v150 offset:32896
	ds_read_b128 v[54:57], v150 offset:32928
	ds_read_b128 v[58:61], v150 offset:32960
	ds_read_b128 v[62:65], v150 offset:32992
	ds_read_b128 v[152:155], v149
	ds_read_b128 v[156:159], v149 offset:512
	s_waitcnt lgkmcnt(4)
	v_pk_add_f32 v[56:57], v[118:119], v[56:57]
	s_waitcnt lgkmcnt(3)
	v_pk_add_f32 v[60:61], v[122:123], v[60:61]
	s_waitcnt lgkmcnt(2)
	v_pk_add_f32 v[64:65], v[126:127], v[64:65]
	v_pk_add_f32 v[52:53], v[114:115], v[52:53]
	v_pk_add_f32 v[62:63], v[124:125], v[62:63]
	v_pk_add_f32 v[58:59], v[120:121], v[58:59]
	v_pk_add_f32 v[54:55], v[116:117], v[54:55]
	v_pk_add_f32 v[50:51], v[112:113], v[50:51]
	v_pk_add_f32 v[48:49], v[126:127], v[48:49]
	v_pk_add_f32 v[44:45], v[122:123], v[44:45]
	v_pk_add_f32 v[40:41], v[118:119], v[40:41]
	v_pk_add_f32 v[36:37], v[114:115], v[36:37]
	v_pk_add_f32 v[46:47], v[124:125], v[46:47]
	v_pk_add_f32 v[42:43], v[120:121], v[42:43]
	v_pk_add_f32 v[38:39], v[116:117], v[38:39]
	v_pk_add_f32 v[34:35], v[112:113], v[34:35]
	s_waitcnt lgkmcnt(0)
	v_mfma_f32_32x32x16_bf16 v[50:65], v[156:159], v[94:97], v[50:65]
	v_mfma_f32_32x32x16_bf16 v[34:49], v[152:155], v[94:97], v[34:49]
	ds_read_b128 v[152:155], v149 offset:2048
	ds_read_b128 v[156:159], v149 offset:2560
	s_waitcnt lgkmcnt(0)
	v_mfma_f32_32x32x16_bf16 v[50:65], v[156:159], v[98:101], v[50:65]
	v_mfma_f32_32x32x16_bf16 v[34:49], v[152:155], v[98:101], v[34:49]
	ds_read_b128 v[152:155], v149 offset:4096
	ds_read_b128 v[156:159], v149 offset:4608
	s_waitcnt lgkmcnt(0)
	v_mfma_f32_32x32x16_bf16 v[50:65], v[156:159], v[102:105], v[50:65]
	v_mfma_f32_32x32x16_bf16 v[34:49], v[152:155], v[102:105], v[34:49]
	ds_read_b128 v[152:155], v149 offset:6656
	ds_read_b128 v[156:159], v149 offset:6144
	s_waitcnt lgkmcnt(1)
	v_mfma_f32_32x32x16_bf16 v[50:65], v[152:155], v[90:93], v[50:65]
	v_add_u32_e32 v152, s75, v142
	v_add_u32_e32 v154, 0xffffff60, v152
	v_add_u32_e32 v153, 0xffffff40, v152
	v_cmp_le_i32_e32 vcc, v154, v147
	s_waitcnt lgkmcnt(0)
	v_mfma_f32_32x32x16_bf16 v[34:49], v[156:159], v[90:93], v[34:49]
	s_nop 5
	v_cndmask_b32_e32 v50, v134, v50, vcc
	v_cmp_lt_i32_e32 vcc, v153, v147
	s_nop 3
	v_cndmask_b32_e32 v35, v134, v35, vcc
	v_cmp_le_i32_e32 vcc, v153, v147
	v_add_u32_e32 v153, 0xffffff61, v152
	v_exp_f32_e32 v35, v35
	v_cndmask_b32_e32 v34, v134, v34, vcc
	v_cmp_le_i32_e32 vcc, v153, v147
	v_add_u32_e32 v153, 0xffffff42, v152
	v_exp_f32_e32 v34, v34
	v_cndmask_b32_e32 v51, v134, v51, vcc
	v_cmp_le_i32_e32 vcc, v153, v147
	s_nop 1
	v_cndmask_b32_e32 v153, v134, v36, vcc
	v_add_u32_e32 v36, 0xffffff62, v152
	v_cmp_le_i32_e32 vcc, v36, v147
	v_add_u32_e32 v36, 0xffffff43, v152
	s_nop 0
	v_cndmask_b32_e32 v52, v134, v52, vcc
	v_cmp_le_i32_e32 vcc, v36, v147
	v_add_u32_e32 v36, 0xffffff63, v152
	s_nop 0
	v_cndmask_b32_e32 v154, v134, v37, vcc
	v_cmp_le_i32_e32 vcc, v36, v147
	v_add_u32_e32 v36, 0xffffff48, v152
	v_exp_f32_e32 v37, v51
	v_cndmask_b32_e32 v53, v134, v53, vcc
	v_cmp_le_i32_e32 vcc, v36, v147
	v_add_u32_e32 v36, 0xffffff68, v152
	s_nop 0
	v_cndmask_b32_e32 v155, v134, v38, vcc
	v_cmp_le_i32_e32 vcc, v36, v147
	v_add_u32_e32 v36, 0xffffff49, v152
	v_exp_f32_e32 v38, v153
	v_cndmask_b32_e32 v54, v134, v54, vcc
	v_cmp_le_i32_e32 vcc, v36, v147
	v_add_u32_e32 v36, 0xffffff69, v152
	s_nop 0
	v_cndmask_b32_e32 v156, v134, v39, vcc
	v_cmp_le_i32_e32 vcc, v36, v147
	v_add_u32_e32 v36, 0xffffff4a, v152
	v_exp_f32_e32 v39, v154
	v_cndmask_b32_e32 v55, v134, v55, vcc
	v_cmp_le_i32_e32 vcc, v36, v147
	v_add_u32_e32 v36, 0xffffff6a, v152
	v_cvt_pk_bf16_f32 v154, v34, v35
	v_cndmask_b32_e32 v157, v134, v40, vcc
	v_cmp_le_i32_e32 vcc, v36, v147
	v_add_u32_e32 v36, 0xffffff4b, v152
	v_exp_f32_e32 v40, v52
	v_cndmask_b32_e32 v56, v134, v56, vcc
	v_cmp_le_i32_e32 vcc, v36, v147
	v_add_u32_e32 v36, 0xffffff6b, v152
	s_nop 0
	v_cndmask_b32_e32 v158, v134, v41, vcc
	v_cmp_le_i32_e32 vcc, v36, v147
	v_add_u32_e32 v36, 0xffffff50, v152
	v_exp_f32_e32 v41, v53
	v_cndmask_b32_e32 v57, v134, v57, vcc
	v_cmp_le_i32_e32 vcc, v36, v147
	v_add_u32_e32 v36, 0xffffff70, v152
	v_exp_f32_e32 v51, v57
	v_cndmask_b32_e32 v159, v134, v42, vcc
	v_cmp_le_i32_e32 vcc, v36, v147
	v_add_u32_e32 v36, 0xffffff51, v152
	v_exp_f32_e32 v52, v159
	v_cndmask_b32_e32 v58, v134, v58, vcc
	v_cmp_le_i32_e32 vcc, v36, v147
	v_add_u32_e32 v36, 0xffffff71, v152
	s_nop 0
	v_cndmask_b32_e32 v160, v134, v43, vcc
	v_cmp_le_i32_e32 vcc, v36, v147
	v_add_u32_e32 v36, 0xffffff52, v152
	v_pk_add_f32 v[42:43], v[34:35], 0 op_sel_hi:[1,0]
	v_cndmask_b32_e32 v59, v134, v59, vcc
	v_cmp_le_i32_e32 vcc, v36, v147
	v_add_u32_e32 v36, 0xffffff72, v152
	v_exp_f32_e32 v53, v160
	v_cndmask_b32_e32 v161, v134, v44, vcc
	v_cmp_le_i32_e32 vcc, v36, v147
	v_add_u32_e32 v36, 0xffffff53, v152
	v_exp_f32_e32 v44, v155
	v_cndmask_b32_e32 v60, v134, v60, vcc
	v_cmp_le_i32_e32 vcc, v36, v147
	v_add_u32_e32 v36, 0xffffff73, v152
	v_cvt_pk_bf16_f32 v155, v38, v39
	v_cndmask_b32_e32 v162, v134, v45, vcc
	v_cmp_le_i32_e32 vcc, v36, v147
	v_add_u32_e32 v36, 0xffffff58, v152
	v_exp_f32_e32 v45, v156
	v_cndmask_b32_e32 v61, v134, v61, vcc
	v_cmp_le_i32_e32 vcc, v36, v147
; __device__ __forceinline__ void pv(f32x16* o, int vb, bf16x8 pa0, bf16x8 pa1, bf16x8 pa2, bf16x8 pa3) {
; #pragma unroll
;     for (int d0 = 0; d0 < 2; ++d0) { s16x4 lo[4], hi[4];
; #pragma unroll
;         for (int ks = 0; ks < 4; ++ks) {
;             asm volatile("ds_read_b64_tr_b16 %0,%1 offset:%c2" : "=&v"(lo[ks]) : "v"(vb), "i"(d0 * 4096 + ks * 1024) : "memory");
;             asm volatile("ds_read_b64_tr_b16 %0,%1 offset:%c2" : "=&v"(hi[ks]) : "v"(vb), "i"(d0 * 4096 + ks * 1024 + 512) : "memory"); }
;         asm volatile("s_waitcnt lgkmcnt(0)" ::: "memory"); __builtin_amdgcn_sched_barrier(0);
;     ...
;         o[d0] = __builtin_amdgcn_mfma_f32_32x32x16_bf16(pa0, PK(0), o[d0], 0, 0, 0);
;         o[d0] = __builtin_amdgcn_mfma_f32_32x32x16_bf16(pa1, PK(1), o[d0], 0, 0, 0);
;         o[d0] = __builtin_amdgcn_mfma_f32_32x32x16_bf16(pa2, PK(2), o[d0], 0, 0, 0);
;         o[d0] = __builtin_amdgcn_mfma_f32_32x32x16_bf16(pa3, PK(3), o[d0], 0, 0, 0);
; template <bool BAND>
; __device__ __forceinline__ void tile_body(f32x16* o, float& l_reg, const bf16x8* qr, const LAS unsigned char* kbs, const LAS float* wb, int vb, float ci, int hi, int keybase, int qabs) {
;     ...
;         for (int r = 0; r < 16; ++r) { const int key = keybase + 8 * (r >> 2) + (r & 3); if (key > qabs) p0[r] = -INFINITY; if (key + 32 > qabs) p1[r] = -INFINITY; }
;     }
;     f32x2 s2 = {0.f, 0.f};
; #pragma unroll
;     for (int r = 0; r < 16; r += 2) {
;         p0[r] = __builtin_amdgcn_exp2f(p0[r]); p0[r + 1] = __builtin_amdgcn_exp2f(p0[r + 1]); p1[r] = __builtin_amdgcn_exp2f(p1[r]); p1[r + 1] = __builtin_amdgcn_exp2f(p1[r + 1]);
;         s2 += (f32x2){p0[r], p0[r + 1]}; s2 += (f32x2){p1[r], p1[r + 1]}; }
;     l_reg += s2.x + s2.y;
;     u32x4 pw0, pw1, pw2, pw3;
;     pw0 = (u32x4){cvtpk(p0[0], p0[1]), cvtpk(p0[2], p0[3]), cvtpk(p0[4], p0[5]), cvtpk(p0[6], p0[7])};
;     pw1 = (u32x4){cvtpk(p0[8], p0[9]), cvtpk(p0[10], p0[11]), cvtpk(p0[12], p0[13]), cvtpk(p0[14], p0[15])};
;     pw2 = (u32x4){cvtpk(p1[0], p1[1]), cvtpk(p1[2], p1[3]), cvtpk(p1[4], p1[5]), cvtpk(p1[6], p1[7])};
;     pw3 = (u32x4){cvtpk(p1[8], p1[9]), cvtpk(p1[10], p1[11]), cvtpk(p1[12], p1[13]), cvtpk(p1[14], p1[15])};
;     pv(o, vb, __builtin_bit_cast(bf16x8, pw0), __builtin_bit_cast(bf16x8, pw1), __builtin_bit_cast(bf16x8, pw2), __builtin_bit_cast(bf16x8, pw3));
	v_add_u32_e32 v36, 0xffffff78, v152
	v_exp_f32_e32 v57, v162
	v_cndmask_b32_e32 v163, v134, v46, vcc
	v_cmp_le_i32_e32 vcc, v36, v147
	v_add_u32_e32 v36, 0xffffff59, v152
	v_exp_f32_e32 v46, v54
	v_cndmask_b32_e32 v62, v134, v62, vcc
	v_cmp_le_i32_e32 vcc, v36, v147
	v_add_u32_e32 v36, 0xffffff79, v152
	v_exp_f32_e32 v54, v58
	v_cndmask_b32_e32 v164, v134, v47, vcc
	v_cmp_le_i32_e32 vcc, v36, v147
	v_add_u32_e32 v36, 0xffffff5a, v152
	v_exp_f32_e32 v47, v55
	v_cndmask_b32_e32 v63, v134, v63, vcc
	v_cmp_le_i32_e32 vcc, v36, v147
	v_add_u32_e32 v36, 0xffffff7a, v152
	v_exp_f32_e32 v55, v59
	v_cndmask_b32_e32 v165, v134, v48, vcc
	v_cmp_le_i32_e32 vcc, v36, v147
	v_add_u32_e32 v36, 0xffffff5b, v152
	v_exp_f32_e32 v48, v157
	v_cndmask_b32_e32 v166, v134, v64, vcc
	v_cmp_le_i32_e32 vcc, v36, v147
	v_add_u32_e32 v36, 0xffffff7b, v152
	v_exp_f32_e32 v58, v60
	v_cndmask_b32_e32 v167, v134, v49, vcc
	v_cmp_le_i32_e32 vcc, v36, v147
	v_exp_f32_e32 v36, v50
	v_exp_f32_e32 v49, v158
	v_exp_f32_e32 v50, v56
	v_exp_f32_e32 v56, v161
	v_pk_add_f32 v[42:43], v[36:37], v[42:43]
	v_exp_f32_e32 v59, v61
	v_pk_add_f32 v[42:43], v[38:39], v[42:43]
	v_exp_f32_e32 v64, v165
	v_pk_add_f32 v[42:43], v[40:41], v[42:43]
	v_cvt_pk_bf16_f32 v165, v50, v51
	v_pk_add_f32 v[42:43], v[44:45], v[42:43]
	v_exp_f32_e32 v60, v163
	v_pk_add_f32 v[42:43], v[46:47], v[42:43]
	v_exp_f32_e32 v61, v164
	v_pk_add_f32 v[42:43], v[48:49], v[42:43]
	v_cvt_pk_bf16_f32 v158, v52, v53
	v_pk_add_f32 v[42:43], v[50:51], v[42:43]
	ds_read_b64_tr_b16 v[50:51],v0 offset:0
	v_exp_f32_e32 v62, v62
	v_pk_add_f32 v[42:43], v[52:53], v[42:43]
	ds_read_b64_tr_b16 v[52:53],v0 offset:512
	v_exp_f32_e32 v63, v63
	v_pk_add_f32 v[42:43], v[54:55], v[42:43]
	v_exp_f32_e32 v170, v166
	v_cvt_pk_bf16_f32 v166, v54, v55
	ds_read_b64_tr_b16 v[54:55],v0 offset:1024
	v_cndmask_b32_e32 v152, v134, v65, vcc
	v_pk_add_f32 v[42:43], v[56:57], v[42:43]
	v_exp_f32_e32 v65, v167
	v_cvt_pk_bf16_f32 v159, v56, v57
	ds_read_b64_tr_b16 v[56:57],v0 offset:1536
	v_pk_add_f32 v[42:43], v[58:59], v[42:43]
	v_exp_f32_e32 v171, v152
	v_cvt_pk_bf16_f32 v167, v58, v59
	ds_read_b64_tr_b16 v[58:59],v0 offset:2048
	v_pk_add_f32 v[42:43], v[60:61], v[42:43]
	v_cvt_pk_bf16_f32 v160, v60, v61
	ds_read_b64_tr_b16 v[60:61],v0 offset:2560
	v_pk_add_f32 v[42:43], v[62:63], v[42:43]
	v_cvt_pk_bf16_f32 v168, v62, v63
	ds_read_b64_tr_b16 v[62:63],v0 offset:3072
	v_pk_add_f32 v[42:43], v[64:65], v[42:43]
	v_cvt_pk_bf16_f32 v161, v64, v65
	ds_read_b64_tr_b16 v[64:65],v0 offset:3584
	v_pk_add_f32 v[42:43], v[170:171], v[42:43]
	s_waitcnt lgkmcnt(0)
	v_cvt_pk_bf16_f32 v156, v44, v45
	v_add_f32_e32 v42, v42, v43
	v_add_f32_e32 v152, v148, v42
	v_cvt_pk_bf16_f32 v157, v48, v49
	v_cvt_pk_bf16_f32 v162, v36, v37
	v_cvt_pk_bf16_f32 v163, v40, v41
	v_cvt_pk_bf16_f32 v164, v46, v47
	v_cvt_pk_bf16_f32 v169, v170, v171
	v_mfma_f32_32x32x16_bf16 v[2:17], v[154:157], v[50:53], v[2:17]
	ds_read_b64_tr_b16 v[170:171],v0 offset:4096
	ds_read_b64_tr_b16 v[172:173],v0 offset:4608
	ds_read_b64_tr_b16 v[174:175],v0 offset:5120
	ds_read_b64_tr_b16 v[176:177],v0 offset:5632
	ds_read_b64_tr_b16 v[178:179],v0 offset:6144
	ds_read_b64_tr_b16 v[180:181],v0 offset:6656
	ds_read_b64_tr_b16 v[182:183],v0 offset:7168
	v_mfma_f32_32x32x16_bf16 v[2:17], v[158:161], v[54:57], v[2:17]
	ds_read_b64_tr_b16 v[184:185],v0 offset:7680
	s_waitcnt lgkmcnt(0)
	v_mfma_f32_32x32x16_bf16 v[2:17], v[162:165], v[58:61], v[2:17]
	v_mfma_f32_32x32x16_bf16 v[2:17], v[166:169], v[62:65], v[2:17]
	v_mfma_f32_32x32x16_bf16 v[18:33], v[154:157], v[170:173], v[18:33]
	s_mov_b64 s[68:69], 0
	v_mfma_f32_32x32x16_bf16 v[18:33], v[158:161], v[174:177], v[18:33]
	v_mfma_f32_32x32x16_bf16 v[18:33], v[162:165], v[178:181], v[18:33]
	v_mfma_f32_32x32x16_bf16 v[18:33], v[166:169], v[182:185], v[18:33]
; #define LAS __attribute__((address_space(3)))
; __device__ __forceinline__ void pv(f32x16* o, int vb, bf16x8 pa0, bf16x8 pa1, bf16x8 pa2, bf16x8 pa3) {
; #pragma unroll
;     for (int d0 = 0; d0 < 2; ++d0) { s16x4 lo[4], hi[4];
; #pragma unroll
;         for (int ks = 0; ks < 4; ++ks) {
; template <bool BAND>
; __device__ __forceinline__ void tile_body(f32x16* o, float& l_reg, const bf16x8* qr, const LAS unsigned char* kbs, const LAS float* wb, int vb, float ci, int hi, int keybase, int qabs) {
;     ...
; #pragma unroll
;     for (int g4 = 0; g4 < 4; ++g4) {
;         const f32x4 ba = *(const LAS f32x4*)(wb + 8 * g4 + 4 * hi) + ci, bb = *(const LAS f32x4*)(wb + 32 + 8 * g4 + 4 * hi) + ci;
; #pragma unroll
;         for (int e = 0; e < 4; ++e) { p0[4 * g4 + e] = ba[e]; p1[4 * g4 + e] = bb[e]; }
;     }
; #pragma unroll
;     for (int d0 = 0; d0 < 4; ++d0) {
;         const bf16x8 b0 = *(const LAS bf16x8*)(kbs + d0 * 2048), b1 = *(const LAS bf16x8*)(kbs + d0 * 2048 + 512);
;         p0 = __builtin_amdgcn_mfma_f32_32x32x16_bf16(b0, qr[d0], p0, 0, 0, 0); p1 = __builtin_amdgcn_mfma_f32_32x32x16_bf16(b1, qr[d0], p1, 0, 0, 0); }
;     if (BAND) {
; #pragma unroll
;         for (int r = 0; r < 16; ++r) { const int key = keybase + 8 * (r >> 2) + (r & 3); if (key > qabs) p0[r] = -INFINITY; if (key + 32 > qabs) p1[r] = -INFINITY; }
;     }
;     f32x2 s2 = {0.f, 0.f};
; #pragma unroll
;     for (int r = 0; r < 16; r += 2) {
;         p0[r] = __builtin_amdgcn_exp2f(p0[r]); p0[r + 1] = __builtin_amdgcn_exp2f(p0[r + 1]); p1[r] = __builtin_amdgcn_exp2f(p1[r]); p1[r + 1] = __builtin_amdgcn_exp2f(p1[r + 1]);
;         s2 += (f32x2){p0[r], p0[r + 1]}; s2 += (f32x2){p1[r], p1[r + 1]}; }
;     l_reg += s2.x + s2.y;
;     u32x4 pw0, pw1, pw2, pw3;
;     pw0 = (u32x4){cvtpk(p0[0], p0[1]), cvtpk(p0[2], p0[3]), cvtpk(p0[4], p0[5]), cvtpk(p0[6], p0[7])};
;     pw1 = (u32x4){cvtpk(p0[8], p0[9]), cvtpk(p0[10], p0[11]), cvtpk(p0[12], p0[13]), cvtpk(p0[14], p0[15])};
;     pw2 = (u32x4){cvtpk(p1[0], p1[1]), cvtpk(p1[2], p1[3]), cvtpk(p1[4], p1[5]), cvtpk(p1[6], p1[7])};
;     pw3 = (u32x4){cvtpk(p1[8], p1[9]), cvtpk(p1[10], p1[11]), cvtpk(p1[12], p1[13]), cvtpk(p1[14], p1[15])};
;     pv(o, vb, __builtin_bit_cast(bf16x8, pw0), __builtin_bit_cast(bf16x8, pw1), __builtin_bit_cast(bf16x8, pw2), __builtin_bit_cast(bf16x8, pw3));
.LBB0_823:
	s_andn2_b64 vcc, exec, s[68:69]
	s_cbranch_vccnz .Lmy_attjoin_C
	s_nop 4
	ds_read_b128 v[34:37], v150 offset:32768
	ds_read_b128 v[38:41], v150 offset:32800
	ds_read_b128 v[42:45], v150 offset:32832
	ds_read_b128 v[46:49], v150 offset:32864
	s_nop 0
	ds_read_b128 v[50:53], v150 offset:32896
	ds_read_b128 v[54:57], v150 offset:32928
	ds_read_b128 v[58:61], v150 offset:32960
	ds_read_b128 v[62:65], v150 offset:32992
	ds_read_b128 v[152:155], v149
	ds_read_b128 v[156:159], v149 offset:512
	s_waitcnt lgkmcnt(6)
	v_pk_add_f32 v[48:49], v[126:127], v[48:49]
	v_pk_add_f32 v[44:45], v[122:123], v[44:45]
	v_pk_add_f32 v[40:41], v[118:119], v[40:41]
	v_pk_add_f32 v[36:37], v[114:115], v[36:37]
	v_pk_add_f32 v[46:47], v[124:125], v[46:47]
	v_pk_add_f32 v[42:43], v[120:121], v[42:43]
	v_pk_add_f32 v[38:39], v[116:117], v[38:39]
	v_pk_add_f32 v[34:35], v[112:113], v[34:35]
	s_waitcnt lgkmcnt(2)
	v_pk_add_f32 v[64:65], v[126:127], v[64:65]
	v_pk_add_f32 v[60:61], v[122:123], v[60:61]
	s_waitcnt lgkmcnt(1)
	v_mfma_f32_32x32x16_bf16 v[34:49], v[152:155], v[94:97], v[34:49]
	v_add_f32_e64 v56, v118, v56
	v_add_f32_e64 v57, v119, v57
	v_add_f32_e64 v52, v114, v52
	v_add_f32_e64 v53, v115, v53
	v_add_f32_e64 v62, v124, v62
	v_add_f32_e64 v63, v125, v63
	v_pk_add_f32 v[58:59], v[120:121], v[58:59]
	v_pk_add_f32 v[54:55], v[116:117], v[54:55]
	v_pk_add_f32 v[50:51], v[112:113], v[50:51]
	s_waitcnt lgkmcnt(0)
	s_nop 0
	v_mfma_f32_32x32x16_bf16 v[50:65], v[156:159], v[94:97], v[50:65]
	ds_read_b128 v[152:155], v149 offset:2048
	ds_read_b128 v[156:159], v149 offset:2560
	s_waitcnt lgkmcnt(1)
	v_mfma_f32_32x32x16_bf16 v[34:49], v[152:155], v[98:101], v[34:49]
	s_waitcnt lgkmcnt(0)
	v_mfma_f32_32x32x16_bf16 v[50:65], v[156:159], v[98:101], v[50:65]
	ds_read_b128 v[152:155], v149 offset:4096
	ds_read_b128 v[156:159], v149 offset:4608
	s_waitcnt lgkmcnt(1)
	v_mfma_f32_32x32x16_bf16 v[34:49], v[152:155], v[102:105], v[34:49]
	s_waitcnt lgkmcnt(0)
	v_mfma_f32_32x32x16_bf16 v[50:65], v[156:159], v[102:105], v[50:65]
	ds_read_b128 v[152:155], v149 offset:6144
	ds_read_b128 v[156:159], v149 offset:6656
	s_waitcnt lgkmcnt(1)
	v_mfma_f32_32x32x16_bf16 v[34:49], v[152:155], v[90:93], v[34:49]
	s_waitcnt lgkmcnt(0)
	v_mfma_f32_32x32x16_bf16 v[50:65], v[156:159], v[90:93], v[50:65]
	s_nop 9
	v_exp_f32_e32 v34, v34
	v_exp_f32_e32 v35, v35
	v_exp_f32_e32 v36, v36
	v_exp_f32_e32 v37, v37
	v_exp_f32_e32 v38, v38
	v_pk_add_f32 v[152:153], v[34:35], 0 op_sel_hi:[1,0]
	v_exp_f32_e32 v39, v39
	v_exp_f32_e32 v50, v50
	v_exp_f32_e32 v51, v51
	v_exp_f32_e32 v52, v52
	v_exp_f32_e32 v53, v53
	v_exp_f32_e32 v54, v54
	v_pk_add_f32 v[152:153], v[50:51], v[152:153]
	v_exp_f32_e32 v55, v55
	v_pk_add_f32 v[152:153], v[36:37], v[152:153]
	v_exp_f32_e32 v40, v40
	v_exp_f32_e32 v41, v41
	v_pk_add_f32 v[152:153], v[52:53], v[152:153]
	v_exp_f32_e32 v56, v56
	v_exp_f32_e32 v57, v57
	v_pk_add_f32 v[152:153], v[38:39], v[152:153]
	v_exp_f32_e32 v42, v42
	v_exp_f32_e32 v43, v43
	v_pk_add_f32 v[152:153], v[54:55], v[152:153]
	v_exp_f32_e32 v58, v58
	v_exp_f32_e32 v59, v59
	v_pk_add_f32 v[152:153], v[40:41], v[152:153]
	v_exp_f32_e32 v44, v44
	v_exp_f32_e32 v45, v45
	v_pk_add_f32 v[152:153], v[56:57], v[152:153]
	v_exp_f32_e32 v60, v60
	v_exp_f32_e32 v61, v61
	v_pk_add_f32 v[152:153], v[42:43], v[152:153]
	v_exp_f32_e32 v46, v46
	v_exp_f32_e32 v47, v47
	v_cvt_pk_bf16_f32 v34, v34, v35
	v_cvt_pk_bf16_f32 v35, v36, v37
	v_cvt_pk_bf16_f32 v36, v38, v39
	v_cvt_pk_bf16_f32 v38, v42, v43
	v_cvt_pk_bf16_f32 v42, v50, v51
	ds_read_b64_tr_b16 v[50:51],v0 offset:0
	v_pk_add_f32 v[152:153], v[58:59], v[152:153]
	v_exp_f32_e32 v62, v62
	v_exp_f32_e32 v63, v63
	v_cvt_pk_bf16_f32 v43, v52, v53
	ds_read_b64_tr_b16 v[52:53],v0 offset:512
	v_pk_add_f32 v[152:153], v[44:45], v[152:153]
	v_exp_f32_e32 v48, v48
	v_exp_f32_e32 v49, v49
	v_cvt_pk_bf16_f32 v39, v44, v45
	v_cvt_pk_bf16_f32 v44, v54, v55
	ds_read_b64_tr_b16 v[54:55],v0 offset:1024
	v_pk_add_f32 v[152:153], v[60:61], v[152:153]
	v_exp_f32_e32 v64, v64
	v_exp_f32_e32 v65, v65
	v_cvt_pk_bf16_f32 v45, v56, v57
	ds_read_b64_tr_b16 v[56:57],v0 offset:1536
	v_pk_add_f32 v[152:153], v[46:47], v[152:153]
	v_cvt_pk_bf16_f32 v37, v40, v41
	v_cvt_pk_bf16_f32 v40, v46, v47
	v_cvt_pk_bf16_f32 v46, v58, v59
	ds_read_b64_tr_b16 v[58:59],v0 offset:2048
	v_pk_add_f32 v[152:153], v[62:63], v[152:153]
	v_cvt_pk_bf16_f32 v47, v60, v61
	ds_read_b64_tr_b16 v[60:61],v0 offset:2560
	v_pk_add_f32 v[152:153], v[48:49], v[152:153]
	v_cvt_pk_bf16_f32 v41, v48, v49
	v_cvt_pk_bf16_f32 v48, v62, v63
	ds_read_b64_tr_b16 v[62:63],v0 offset:3072
	v_pk_add_f32 v[152:153], v[64:65], v[152:153]
	v_cvt_pk_bf16_f32 v49, v64, v65
	ds_read_b64_tr_b16 v[64:65],v0 offset:3584
	s_waitcnt lgkmcnt(0)
	v_add_f32_e32 v149, v152, v153
	v_add_f32_e32 v152, v148, v149
	v_mfma_f32_32x32x16_bf16 v[2:17], v[34:37], v[50:53], v[2:17]
	ds_read_b64_tr_b16 v[50:51],v0 offset:4096
	ds_read_b64_tr_b16 v[52:53],v0 offset:4608
	v_mfma_f32_32x32x16_bf16 v[2:17], v[38:41], v[54:57], v[2:17]
	ds_read_b64_tr_b16 v[54:55],v0 offset:5120
	ds_read_b64_tr_b16 v[56:57],v0 offset:5632
	v_mfma_f32_32x32x16_bf16 v[2:17], v[42:45], v[58:61], v[2:17]
	ds_read_b64_tr_b16 v[58:59],v0 offset:6144
	ds_read_b64_tr_b16 v[60:61],v0 offset:6656
	ds_read_b64_tr_b16 v[154:155],v0 offset:7168
	ds_read_b64_tr_b16 v[156:157],v0 offset:7680
	s_waitcnt lgkmcnt(0)
	v_mfma_f32_32x32x16_bf16 v[2:17], v[46:49], v[62:65], v[2:17]
	v_mfma_f32_32x32x16_bf16 v[18:33], v[34:37], v[50:53], v[18:33]
	v_mfma_f32_32x32x16_bf16 v[18:33], v[38:41], v[54:57], v[18:33]
	v_mfma_f32_32x32x16_bf16 v[18:33], v[42:45], v[58:61], v[18:33]
	v_mfma_f32_32x32x16_bf16 v[18:33], v[46:49], v[154:157], v[18:33]
	s_branch .Lmy_attjoin_C

; #define LAS __attribute__((address_space(3)))
; __device__ __forceinline__ void attn_unit(const UnitDesc& u, LAS unsigned char* shm, float qkmax, float thresh) {
;     ...
;     asm volatile("s_waitcnt vmcnt(0)" : "+v"(kA), "+v"(vA), "+v"(kB), "+v"(vB), "+v"(kC), "+v"(vC), "+v"(lA), "+v"(lB), "+v"(lC) :: "memory");
;     if (active) {
;         u32x4 zv4[4];
; #pragma unroll
;         for (int i = 0; i < 4; ++i) zv4[i] = *(const u32x4*)(u.Zg + (size_t)(wid * 32 + i * 8 + (lane >> 3)) * 512 + (lane & 7) * 8);
;         { auto rr = __builtin_amdgcn_permlane32_swap(__float_as_uint(l_reg), __float_as_uint(l_reg), false, false); l_reg = __uint_as_float(rr[0]) + __uint_as_float(rr[1]); }
;         LAS float* lx = (LAS float*)(shm + LDS_LX) + wid * 32;
;         if (hi == 0) lx[r32] = l_reg;
.LBB0_829:
	s_or_b64 exec, exec, s[62:63]
	s_waitcnt vmcnt(0)
	s_and_b64 vcc, exec, s[12:13]
	s_cbranch_vccnz .LBB0_719
	s_nop 7
	s_nop 7
	v_mov_b64_e32 v[34:35], v[2:3]
	v_mov_b64_e32 v[36:37], v[4:5]
	v_mov_b64_e32 v[38:39], v[6:7]
	v_mov_b64_e32 v[40:41], v[8:9]
	v_mov_b64_e32 v[42:43], v[10:11]
	v_mov_b64_e32 v[44:45], v[12:13]
	v_mov_b64_e32 v[46:47], v[14:15]
	v_mov_b64_e32 v[48:49], v[16:17]
	v_mov_b64_e32 v[50:51], v[18:19]
	v_mov_b64_e32 v[52:53], v[20:21]
	v_mov_b64_e32 v[54:55], v[22:23]
	v_mov_b64_e32 v[56:57], v[24:25]
	v_mov_b64_e32 v[58:59], v[26:27]
	v_mov_b64_e32 v[60:61], v[28:29]
	v_mov_b64_e32 v[62:63], v[30:31]
	v_mov_b64_e32 v[64:65], v[32:33]
	s_lshl_b64 s[6:7], s[44:45], 1
	s_add_u32 s8, s24, s6
	v_lshrrev_b32_e32 v20, 3, v137
	s_addc_u32 s9, s25, s7
	s_lshl_b64 s[6:7], s[46:47], 1
	v_or_b32_e32 v18, s49, v20
	s_add_u32 s8, s8, s6
	v_and_b32_e32 v0, 56, v138
	v_or_b32_e32 v6, 8, v18
	s_addc_u32 s9, s9, s7
	v_lshlrev_b32_e32 v0, 1, v0
	v_ashrrev_i32_e32 v19, 31, v18
	v_ashrrev_i32_e32 v7, 31, v6
	v_lshl_add_u64 v[2:3], s[8:9], 0, v[0:1]
	v_lshlrev_b64 v[4:5], 10, v[18:19]
	v_lshlrev_b64 v[6:7], 10, v[6:7]
	v_lshl_add_u64 v[4:5], v[2:3], 0, v[4:5]
	v_lshl_add_u64 v[6:7], v[2:3], 0, v[6:7]
	global_load_dwordx4 v[14:17], v[4:5], off
	global_load_dwordx4 v[10:13], v[6:7], off
	v_or_b32_e32 v4, 16, v18
	v_or_b32_e32 v6, 24, v18
	v_ashrrev_i32_e32 v5, 31, v4
	v_ashrrev_i32_e32 v7, 31, v6
	v_lshlrev_b64 v[4:5], 10, v[4:5]
	v_lshlrev_b64 v[6:7], 10, v[6:7]
	v_lshl_add_u64 v[4:5], v[2:3], 0, v[4:5]
	v_lshl_add_u64 v[2:3], v[2:3], 0, v[6:7]
	global_load_dwordx4 v[6:9], v[4:5], off
	s_nop 0
	global_load_dwordx4 v[2:5], v[2:3], off
	v_mov_b32_e32 v21, v148
	s_lshl_b32 s8, s49, 2
	s_nop 0
	v_permlane32_swap_b32_e32 v148, v21
	s_add_i32 s10, s8, 0
	v_cmp_gt_u32_e32 vcc, 32, v137
	s_and_saveexec_b64 s[8:9], vcc
	s_cbranch_execz .LBB0_718
	v_add_f32_e32 v21, v148, v21
	v_lshl_add_u32 v22, v135, 2, s10
	ds_write_b32 v22, v21 offset:36864
	s_branch .LBB0_718
